# speedup vs baseline: 1.0081x; 1.0019x over previous
; __device__ __forceinline__ void scan_phase(const ScanArgs& s, char* shm) {
;     ...
;   for (int item = bid; item < 256; item += gridDim.x) {
;     ...
;     __syncthreads();
;   }
.LBB0_126:
	s_setprio 0
	s_or_b64 exec, exec, s[54:55]
	s_waitcnt lgkmcnt(0)
	s_barrier
	s_load_dword s49, s[72:73], 0x0
	s_waitcnt lgkmcnt(0)
	s_add_i32 s38, s49, s38
	s_cmpk_gt_i32 s38, 0xff
	s_cbranch_scc1 .LBB0_174

; #define LDSP(p) ((__attribute__((address_space(3))) unsigned*)(p))
; #define SCAN_BAR() do { asm volatile("s_waitcnt lgkmcnt(0)" ::: "memory"); __builtin_amdgcn_s_barrier(); asm volatile("" ::: "memory"); } while (0)
; __device__ __forceinline__ void scan_phase(const ScanArgs& s, char* shm) {
;     ...
;     if (wid < 2) {
;       const int rr = lane >> 4, j = lane & 15, row = wid * 4 + rr;
;       float S0 = 0.f, S1 = 0.f, S2 = 0.f, S3 = 0.f, d1 = 0.f, ppv = 0.f, Gp = 0.f;
;       const unsigned lds0 = (unsigned)(size_t)LDSP(shm);
;       SCAN_BAR();
.LBB0_169:
	s_andn2_saveexec_b64 s[54:55], s[54:55]
	s_cbranch_execz .LBB0_126
	s_waitcnt lgkmcnt(0)
	s_barrier
	s_setprio 3
	v_mov_b32_e32 v0, 0
	v_mov_b32_e32 v1, 0
	v_mov_b32_e32 v2, 0
	v_mov_b32_e32 v3, 0
	v_mov_b32_e32 v4, 0
	v_mov_b32_e32 v5, 0
	v_mov_b32_e32 v6, 0
	v_mov_b32_e32 v7, 0
	v_mov_b32_e32 v67, 0
	s_mov_b32 s49, 0
	s_mov_b32 s56, 0
	s_branch .LBB0_172
